# attention loop: K/V prefetch with per-lane 32-bit offsets and scalar tile bases (12 fewer VALU per iteration), on top of the conversion-slice rewrite
# speedup vs baseline: 1.0124x; 1.0028x over previous
.LBB0_429:
	s_min_i32 s48, s25, 0x43
	v_lshlrev_b32_e32 v188, 3, v0
	v_mad_i64_i32 v[100:101], s[4:5], v98, s38, 0
	v_add_u32_e32 v193, 0, v190
	v_mad_u32_u24 v42, v218, s41, v193
	ds_read_b128 v[36:39], v42
	ds_read_b128 v[48:51], v42 offset:32
	ds_read_b128 v[52:55], v42 offset:64
	ds_read_b128 v[56:59], v42 offset:96
	ds_read_b128 v[60:63], v42 offset:4608
	ds_read_b128 v[102:105], v42 offset:4640
	ds_read_b128 v[106:109], v42 offset:4672
	s_waitcnt lgkmcnt(0)
	v_mfma_f32_32x32x16_bf16 v[0:15], v[36:39], v[132:135], 0
	ds_read_b128 v[110:113], v42 offset:4704
	v_add_co_u32_e32 v40, vcc, 0x2000, v34
	v_sub_u32_e32 v187, v193, v188
	s_nop 0
	v_addc_co_u32_e32 v41, vcc, 0, v35, vcc
	v_add_co_u32_e32 v34, vcc, 0x3000, v34
	v_mfma_f32_32x32x16_bf16 v[16:31], v[60:63], v[132:135], 0
	s_nop 0
	v_addc_co_u32_e32 v35, vcc, 0, v35, vcc
	global_load_dwordx4 v[84:87], v[40:41], off
	global_load_dwordx4 v[80:83], v[32:33], off offset:128
	v_add_co_u32_e32 v32, vcc, 0x44000, v32
	v_and_b32_e32 v41, 64, v181
	s_nop 0
	v_addc_co_u32_e32 v33, vcc, 0, v33, vcc
	v_mfma_f32_32x32x16_bf16 v[0:15], v[48:51], v[156:159], v[0:15]
	v_xor_b32_e32 v40, 32, v181
	v_add_u32_e32 v41, 64, v41
	v_cmp_lt_i32_e32 vcc, v40, v41
	global_load_dwordx4 v[92:95], v[34:35], off
	global_load_dwordx4 v[88:91], v[32:33], off offset:128
	v_cndmask_b32_e32 v40, v181, v40, vcc
	v_lshlrev_b32_e32 v191, 2, v40
	v_mul_u32_u24_e32 v215, 0x90, v218
	v_mfma_f32_32x32x16_bf16 v[16:31], v[102:105], v[156:159], v[16:31]
	s_mov_b32 s50, 2
	s_movk_i32 s52, 0x4000
	v_mfma_f32_32x32x16_bf16 v[0:15], v[52:55], v[152:155], v[0:15]
	v_mfma_f32_32x32x16_bf16 v[16:31], v[106:109], v[152:155], v[16:31]
	s_waitcnt lgkmcnt(0)
	v_mfma_f32_32x32x16_bf16 v[16:31], v[110:113], v[148:151], v[16:31]
	v_mfma_f32_32x32x16_bf16 v[0:15], v[56:59], v[148:151], v[0:15]
	s_nop 10
	v_max_f32_e32 v40, v16, v16
	v_max_f32_e32 v41, v0, v0
	v_max_f32_e32 v40, v41, v40
	v_max3_f32 v40, v40, v1, v17
	v_max3_f32 v40, v40, v2, v18
	v_max3_f32 v40, v40, v3, v19
	v_max3_f32 v40, v40, v4, v20
	v_max3_f32 v40, v40, v5, v21
	v_max3_f32 v40, v40, v6, v22
	v_max3_f32 v40, v40, v7, v23
	v_max3_f32 v40, v40, v8, v24
	v_max3_f32 v40, v40, v9, v25
	v_max3_f32 v40, v40, v10, v26
	v_max3_f32 v40, v40, v11, v27
	v_max3_f32 v40, v40, v12, v28
	v_max3_f32 v40, v40, v13, v29
	v_max3_f32 v40, v40, v14, v30
	v_max3_f32 v40, v40, v15, v31
	ds_bpermute_b32 v41, v191, v40
	s_waitcnt lgkmcnt(0)
	v_max3_f32 v64, v40, v41, s43
	v_cmp_lt_f32_e32 vcc, s43, v64
	s_cmp_eq_u64 vcc, 0
	v_sub_f32_e32 v32, 0xf149f2ca, v64
	s_cselect_b64 vcc, -1, 0
	v_exp_f32_e32 v220, v32
	s_waitcnt vmcnt(0)
	v_mfma_f32_32x32x16_bf16 v[32:47], v[36:39], v[172:175], 0
	v_cndmask_b32_e32 v216, v64, v214, vcc
	v_sub_f32_e32 v1, v1, v216
	v_sub_f32_e32 v0, v0, v216
	v_exp_f32_e32 v202, v0
	v_exp_f32_e32 v200, v1
	v_sub_f32_e32 v16, v16, v216
	v_exp_f32_e32 v136, v16
	v_mfma_f32_32x32x16_bf16 v[64:79], v[60:63], v[172:175], 0
	v_sub_f32_e32 v7, v7, v216
	v_sub_f32_e32 v6, v6, v216
	v_sub_f32_e32 v5, v5, v216
	v_sub_f32_e32 v4, v4, v216
	v_sub_f32_e32 v3, v3, v216
	v_sub_f32_e32 v2, v2, v216
	v_exp_f32_e32 v210, v2
	v_mfma_f32_32x32x16_bf16 v[32:47], v[48:51], v[168:171], v[32:47]
	v_exp_f32_e32 v208, v3
	v_exp_f32_e32 v206, v4
	v_exp_f32_e32 v204, v5
	v_exp_f32_e32 v198, v6
	v_exp_f32_e32 v196, v7
	v_sub_f32_e32 v15, v15, v216
	v_sub_f32_e32 v14, v14, v216
	v_mfma_f32_32x32x16_bf16 v[64:79], v[102:105], v[168:171], v[64:79]
	v_sub_f32_e32 v13, v13, v216
	v_sub_f32_e32 v12, v12, v216
	v_sub_f32_e32 v11, v11, v216
	v_sub_f32_e32 v10, v10, v216
	v_sub_f32_e32 v9, v9, v216
	v_sub_f32_e32 v8, v8, v216
	v_sub_f32_e32 v31, v31, v216
	v_mfma_f32_32x32x16_bf16 v[32:47], v[52:55], v[164:167], v[32:47]
	v_sub_f32_e32 v30, v30, v216
	v_sub_f32_e32 v29, v29, v216
	v_sub_f32_e32 v28, v28, v216
	v_sub_f32_e32 v27, v27, v216
	v_sub_f32_e32 v26, v26, v216
	v_sub_f32_e32 v25, v25, v216
	v_sub_f32_e32 v24, v24, v216
	v_mfma_f32_32x32x16_bf16 v[64:79], v[106:109], v[164:167], v[64:79]
	v_sub_f32_e32 v23, v23, v216
	v_sub_f32_e32 v22, v22, v216
	v_sub_f32_e32 v21, v21, v216
	v_sub_f32_e32 v20, v20, v216
	v_sub_f32_e32 v19, v19, v216
	v_sub_f32_e32 v18, v18, v216
	v_sub_f32_e32 v17, v17, v216
	v_mfma_f32_32x32x16_bf16 v[32:47], v[56:59], v[160:163], v[32:47]
	v_exp_f32_e32 v194, v8
	v_exp_f32_e32 v178, v9
	v_exp_f32_e32 v176, v10
	v_exp_f32_e32 v146, v11
	v_exp_f32_e32 v144, v12
	v_exp_f32_e32 v142, v13
	v_exp_f32_e32 v140, v14
	v_mfma_f32_32x32x16_bf16 v[64:79], v[110:113], v[160:163], v[64:79]
	s_nop 3
	v_max_f32_e32 v1, v32, v32
	v_exp_f32_e32 v138, v15
	v_exp_f32_e32 v130, v17
	v_exp_f32_e32 v128, v18
	v_exp_f32_e32 v116, v19
	v_exp_f32_e32 v114, v20
	v_exp_f32_e32 v112, v21
	s_nop 0
	v_max_f32_e32 v0, v64, v64
	v_max_f32_e32 v0, v1, v0
	v_max3_f32 v0, v0, v33, v65
	v_max3_f32 v0, v0, v34, v66
	v_max3_f32 v0, v0, v35, v67
	v_max3_f32 v0, v0, v36, v68
	v_max3_f32 v0, v0, v37, v69
	v_max3_f32 v0, v0, v38, v70
	v_max3_f32 v0, v0, v39, v71
	v_max3_f32 v0, v0, v40, v72
	v_max3_f32 v0, v0, v41, v73
	v_max3_f32 v0, v0, v42, v74
	v_max3_f32 v0, v0, v43, v75
	v_max3_f32 v0, v0, v44, v76
	v_max3_f32 v0, v0, v45, v77
	v_max3_f32 v0, v0, v46, v78
	v_max3_f32 v0, v0, v47, v79
	ds_bpermute_b32 v1, v191, v0
	v_exp_f32_e32 v110, v22
	v_exp_f32_e32 v108, v23
	v_exp_f32_e32 v106, v24
	v_exp_f32_e32 v104, v25
	s_waitcnt lgkmcnt(0)
	v_max3_f32 v48, v0, v1, s43
	v_sub_f32_e32 v0, 0xf149f2ca, v48
	v_exp_f32_e32 v221, v0
	v_cmp_lt_f32_e64 s[4:5], s43, v48
	s_cmp_eq_u64 s[4:5], 0
	v_exp_f32_e32 v102, v26
	v_pk_mul_f32 v[0:1], v[220:221], 0 op_sel_hi:[1,0]
	v_exp_f32_e32 v124, v27
	v_cndmask_b32_e64 v16, v0, 0, vcc
	s_cselect_b64 vcc, -1, 0
	v_cndmask_b32_e32 v217, v48, v214, vcc
	v_sub_f32_e32 v32, v32, v217
	v_exp_f32_e32 v203, v32
	v_mad_u32_u24 v32, v218, s44, v187
	v_add_u32_e32 v233, 0x2000, v32
	v_sub_f32_e32 v121, v77, v217
	v_sub_f32_e32 v123, v76, v217
	v_sub_f32_e32 v125, v75, v217
	v_sub_f32_e32 v219, v74, v217
	ds_read2_b64 v[74:77], v233 offset0:128 offset1:130
	v_sub_f32_e32 v39, v39, v217
	v_sub_f32_e32 v38, v38, v217
	v_sub_f32_e32 v37, v37, v217
	v_sub_f32_e32 v36, v36, v217
	v_sub_f32_e32 v35, v35, v217
	v_sub_f32_e32 v34, v34, v217
	v_sub_f32_e32 v33, v33, v217
	v_exp_f32_e32 v201, v33
	v_exp_f32_e32 v211, v34
	v_exp_f32_e32 v209, v35
	v_exp_f32_e32 v207, v36
	v_exp_f32_e32 v205, v37
	v_exp_f32_e32 v199, v38
	v_exp_f32_e32 v197, v39
	v_cndmask_b32_e64 v0, v1, 0, vcc
	v_exp_f32_e32 v122, v28
	v_exp_f32_e32 v120, v29
	v_exp_f32_e32 v118, v30
	v_exp_f32_e32 v126, v31
	v_mov_b32_e32 v17, v16
	v_mov_b32_e32 v18, v16
	v_mov_b32_e32 v19, v16
	v_mov_b32_e32 v20, v16
	v_mov_b32_e32 v21, v16
	v_mov_b32_e32 v22, v16
	v_mov_b32_e32 v23, v16
	v_mov_b32_e32 v24, v16
	v_mov_b32_e32 v25, v16
	v_mov_b32_e32 v26, v16
	v_mov_b32_e32 v27, v16
	v_mov_b32_e32 v28, v16
	v_mov_b32_e32 v29, v16
	v_mov_b32_e32 v30, v16
	v_mov_b32_e32 v31, v16
	v_mov_b32_e32 v1, v0
	v_mov_b32_e32 v2, v0
	v_mov_b32_e32 v3, v0
	v_mov_b32_e32 v4, v0
	v_mov_b32_e32 v5, v0
	v_mov_b32_e32 v6, v0
	v_mov_b32_e32 v7, v0
	v_mov_b32_e32 v8, v0
	v_mov_b32_e32 v9, v0
	v_mov_b32_e32 v10, v0
	v_mov_b32_e32 v11, v0
	v_mov_b32_e32 v12, v0
	v_mov_b32_e32 v13, v0
	v_mov_b32_e32 v14, v0
	v_mov_b32_e32 v15, v0
	v_cvt_pk_bf16_f32 v220, v202, v200
	v_cvt_pk_bf16_f32 v221, v210, v208
	v_cvt_pk_bf16_f32 v222, v206, v204
	v_cvt_pk_bf16_f32 v223, v198, v196
	v_cvt_pk_bf16_f32 v224, v203, v201
	v_cvt_pk_bf16_f32 v225, v211, v209
	v_cvt_pk_bf16_f32 v226, v207, v205
	v_cvt_pk_bf16_f32 v227, v199, v197
	v_sub_f32_e32 v238, v69, v217
	v_sub_f32_e32 v239, v68, v217
	v_sub_f32_e32 v240, v67, v217
	v_sub_f32_e32 v129, v66, v217
	ds_read2_b64 v[66:69], v233 offset0:132 offset1:134
	v_sub_f32_e32 v103, v47, v217
	v_sub_f32_e32 v105, v46, v217
	v_sub_f32_e32 v107, v45, v217
	v_sub_f32_e32 v109, v44, v217
	v_sub_f32_e32 v111, v43, v217
	v_sub_f32_e32 v113, v42, v217
	v_sub_f32_e32 v115, v41, v217
	v_sub_f32_e32 v117, v40, v217
	s_waitcnt lgkmcnt(1)
	v_mfma_f32_32x32x16_bf16 v[48:63], v[74:77], v[220:223], v[16:31]
	v_add_u32_e32 v234, 0x3000, v32
	v_exp_f32_e32 v195, v117
	v_exp_f32_e32 v179, v115
	v_exp_f32_e32 v177, v113
	v_exp_f32_e32 v147, v111
	v_exp_f32_e32 v145, v109
	v_exp_f32_e32 v143, v107
	v_mfma_f32_32x32x16_bf16 v[32:47], v[74:77], v[224:227], v[0:15]
	v_exp_f32_e32 v141, v105
	v_exp_f32_e32 v139, v103
	ds_read2_b64 v[228:231], v234 offset0:160 offset1:162
	v_sub_f32_e32 v127, v79, v217
	v_sub_f32_e32 v119, v78, v217
	v_sub_f32_e32 v232, v73, v217
	v_sub_f32_e32 v235, v72, v217
	v_sub_f32_e32 v236, v71, v217
	v_sub_f32_e32 v237, v70, v217
	v_mov_b32_e32 v78, v16
	v_mov_b32_e32 v79, v0
	v_cvt_pk_bf16_f32 v70, v194, v178
	v_cvt_pk_bf16_f32 v71, v176, v146
	v_cvt_pk_bf16_f32 v72, v144, v142
	v_cvt_pk_bf16_f32 v73, v140, v138
	v_cvt_pk_bf16_f32 v74, v195, v179
	v_cvt_pk_bf16_f32 v75, v177, v147
	v_cvt_pk_bf16_f32 v76, v145, v143
	v_cvt_pk_bf16_f32 v77, v141, v139
	v_sub_f32_e32 v131, v65, v217
	s_waitcnt lgkmcnt(1)
	v_mfma_f32_32x32x16_bf16 v[48:63], v[66:69], v[70:73], v[48:63]
	v_exp_f32_e32 v131, v131
	v_exp_f32_e32 v129, v129
	v_exp_f32_e32 v117, v240
	v_exp_f32_e32 v115, v239
	v_exp_f32_e32 v113, v238
	v_exp_f32_e32 v111, v237
	v_exp_f32_e32 v109, v236
	v_mfma_f32_32x32x16_bf16 v[32:47], v[66:69], v[74:77], v[32:47]
	v_sub_f32_e32 v66, v64, v217
	v_add_f32_e64 v64, v78, v202
	v_add_f32_e64 v65, v79, v203
	v_exp_f32_e32 v137, v66
	v_pk_add_f32 v[64:65], v[200:201], v[64:65]
	v_cvt_pk_bf16_f32 v68, v136, v130
	v_pk_add_f32 v[64:65], v[210:211], v[64:65]
	v_cvt_pk_bf16_f32 v69, v128, v116
	v_pk_add_f32 v[64:65], v[208:209], v[64:65]
	s_waitcnt lgkmcnt(0)
	v_mfma_f32_32x32x16_bf16 v[16:31], v[228:231], v[220:223], v[16:31]
	v_add_f32_e64 v64, v206, v64
	v_add_f32_e64 v65, v207, v65
	ds_read2_b64 v[220:223], v234 offset0:164 offset1:166
	v_add_f32_e64 v64, v204, v64
	v_add_f32_e64 v65, v205, v65
	v_exp_f32_e32 v107, v235
	v_pk_add_f32 v[64:65], v[198:199], v[64:65]
	v_exp_f32_e32 v105, v232
	v_pk_add_f32 v[64:65], v[196:197], v[64:65]
	v_mfma_f32_32x32x16_bf16 v[0:15], v[228:231], v[224:227], v[0:15]
	v_add_f32_e64 v194, v194, v64
	v_add_f32_e64 v195, v195, v65
	ds_read2_b64 v[64:67], v233 offset0:136 offset1:138
	v_exp_f32_e32 v103, v219
	v_exp_f32_e32 v125, v125
	v_exp_f32_e32 v123, v123
	v_exp_f32_e32 v121, v121
	v_exp_f32_e32 v119, v119
	s_waitcnt lgkmcnt(1)
	v_mfma_f32_32x32x16_bf16 v[16:31], v[220:223], v[70:73], v[16:31]
	v_cvt_pk_bf16_f32 v70, v114, v112
	v_cvt_pk_bf16_f32 v71, v110, v108
	v_cvt_pk_bf16_f32 v72, v137, v131
	v_cvt_pk_bf16_f32 v73, v129, v117
	v_exp_f32_e32 v127, v127
	v_mad_u64_u32 v[196:197], s[4:5], v98, s44, v[182:183]
	v_mfma_f32_32x32x16_bf16 v[0:15], v[220:223], v[74:77], v[0:15]
	v_cvt_pk_bf16_f32 v74, v115, v113
	v_cvt_pk_bf16_f32 v75, v111, v109
	ds_read2_b64 v[76:79], v234 offset0:168 offset1:170
	s_add_i32 s0, s31, 1
	v_readlane_b32 s4, v255, 0
	s_mul_i32 s51, s33, s0
	s_mov_b32 s53, s4
	s_waitcnt lgkmcnt(1)
	v_mfma_f32_32x32x16_bf16 v[48:63], v[64:67], v[68:71], v[48:63]
	v_readlane_b32 s5, v255, 1
	v_mfma_f32_32x32x16_bf16 v[32:47], v[64:67], v[72:75], v[32:47]
	v_add_f32_e64 v64, v178, v194
	v_add_f32_e64 v65, v179, v195
	v_add_f32_e64 v64, v176, v64
	v_add_f32_e64 v65, v177, v65
	v_add_f32_e64 v64, v146, v64
	v_add_f32_e64 v65, v147, v65
	v_pk_add_f32 v[64:65], v[144:145], v[64:65]
	s_waitcnt lgkmcnt(0)
	v_mfma_f32_32x32x16_bf16 v[16:31], v[76:79], v[68:71], v[16:31]
	v_add_f32_e64 v64, v142, v64
	v_add_f32_e64 v65, v143, v65
	v_cvt_pk_bf16_f32 v68, v106, v104
	v_add_f32_e64 v64, v140, v64
	v_add_f32_e64 v65, v141, v65
	v_cvt_pk_bf16_f32 v69, v102, v124
	v_pk_add_f32 v[64:65], v[138:139], v[64:65]
	v_cvt_pk_bf16_f32 v70, v122, v120
	v_pk_add_f32 v[64:65], v[136:137], v[64:65]
	v_mfma_f32_32x32x16_bf16 v[0:15], v[76:79], v[72:75], v[0:15]
	v_add_f32_e64 v64, v130, v64
	v_add_f32_e64 v65, v131, v65
	v_cvt_pk_bf16_f32 v71, v118, v126
	v_add_f32_e64 v128, v128, v64
	v_add_f32_e64 v129, v129, v65
	ds_read2_b64 v[64:67], v233 offset0:140 offset1:142
	v_cvt_pk_bf16_f32 v72, v107, v105
	v_cvt_pk_bf16_f32 v73, v103, v125
	v_cvt_pk_bf16_f32 v74, v123, v121
	v_cvt_pk_bf16_f32 v75, v119, v127
	s_waitcnt lgkmcnt(0)
	v_mfma_f32_32x32x16_bf16 v[48:63], v[64:67], v[68:71], v[48:63]
	ds_read2_b64 v[76:79], v234 offset0:172 offset1:174
	v_mfma_f32_32x32x16_bf16 v[32:47], v[64:67], v[72:75], v[32:47]
	v_add_f32_e64 v64, v116, v128
	v_add_f32_e64 v65, v117, v129
	v_add_f32_e64 v64, v114, v64
	v_add_f32_e64 v65, v115, v65
	v_add_f32_e64 v64, v112, v64
	v_add_f32_e64 v65, v113, v65
	v_pk_add_f32 v[64:65], v[110:111], v[64:65]
	s_waitcnt lgkmcnt(0)
	v_mfma_f32_32x32x16_bf16 v[16:31], v[76:79], v[68:71], v[16:31]
	v_add_f32_e64 v64, v108, v64
	v_add_f32_e64 v65, v109, v65
	v_add_f32_e64 v64, v106, v64
	v_add_f32_e64 v65, v107, v65
	v_add_f32_e64 v64, v104, v64
	v_add_f32_e64 v65, v105, v65
	v_pk_add_f32 v[64:65], v[102:103], v[64:65]
	v_mfma_f32_32x32x16_bf16 v[0:15], v[76:79], v[72:75], v[0:15]
	v_add_f32_e64 v64, v124, v64
	v_add_f32_e64 v65, v125, v65
	v_add_f32_e64 v64, v122, v64
	v_add_f32_e64 v65, v123, v65
	v_add_f32_e64 v64, v120, v64
	v_add_f32_e64 v65, v121, v65
	v_pk_add_f32 v[64:65], v[118:119], v[64:65]
	s_nop 0
	v_pk_add_f32 v[194:195], v[126:127], v[64:65]
	v_add_u32_e32 v64, 0, v196
	v_add_u32_e32 v66, 0x6a00, v64
	v_add_u32_e32 v64, 0x7b00, v64
	ds_write_b128 v99, v[84:87] offset:17920
	ds_write_b128 v99, v[92:95] offset:22528
	ds_write2_b64 v66, v[80:81], v[82:83] offset1:1
	ds_write2_b64 v64, v[88:89], v[90:91] offset1:1
	v_and_b32_e32 v64, 7, v189
	v_lshlrev_b32_e32 v182, 4, v64
	s_waitcnt vmcnt(0)
	v_lshl_add_u64 v[66:67], v[96:97], 0, v[182:183]
	v_lshl_add_u64 v[198:199], s[94:95], 0, v[66:67]
	v_lshl_add_u64 v[66:67], v[100:101], 0, v[182:183]
	v_mul_u32_u24_e32 v65, 0x88, v218
	v_lshl_add_u64 v[200:201], s[94:95], 0, v[66:67]
	s_waitcnt lgkmcnt(0)
	s_barrier
	v_lshrrev_b32_e32 v241, 4, v189
	v_and_b32_e32 v242, 15, v189
	v_bfe_u32 v245, v189, 7, 1
	v_xor_b32_e32 v242, v242, v245
	v_lshlrev_b32_e32 v242, 4, v242
	v_lshrrev_b32_e32 v245, 6, v189
	v_lshlrev_b32_e32 v245, 10, v245
	v_and_b32_e32 v244, 7, v189
	v_readfirstlane_b32 s98, v245
	v_lshrrev_b32_e32 v243, 5, v189
	v_xor_b32_e32 v243, v243, v244
	v_and_b32_e32 v243, 15, v243
	v_lshlrev_b32_e32 v243, 4, v243
	v_bfe_u32 v245, v189, 3, 2
	v_lshl_add_u32 v243, v245, 2, v243
	v_lshl_add_u32 v243, v244, 11, v243
	v_lshrrev_b32_e32 v245, 3, v189
	v_lshlrev_b32_e32 v245, 11, v245
	v_lshl_add_u32 v244, v244, 4, v245
	v_subrev_u32_e32 v246, s94, v198
	v_subrev_u32_e32 v247, s94, v200
	s_add_u32 s60, s94, s16
	s_addc_u32 s61, s95, s17
	s_add_u32 s64, s60, 0xe3de100
	s_addc_u32 s65, s61, 0
	s_add_u32 s66, s60, 0xe422100
	s_addc_u32 s67, s61, 0
	s_add_u32 s62, s60, 0xdee3000
	s_addc_u32 s63, s61, 0
	s_add_u32 s60, s60, 0xdee2000
	s_addc_u32 s61, s61, 0

.LBB0_452:
	s_setprio 2
	v_add3_u32 v197, s54, v190, v215
	ds_read_b128 v[68:71], v197
	ds_read_b128 v[72:75], v197 offset:32
	ds_read_b128 v[76:79], v197 offset:64
	ds_read_b128 v[80:83], v197 offset:96
	ds_read_b128 v[84:87], v197 offset:4608
	ds_read_b128 v[88:91], v197 offset:4640
	ds_read_b128 v[92:95], v197 offset:4672
	ds_read_b128 v[96:99], v197 offset:4704
	global_load_dwordx4 v[136:139], v246, s[60:61]
	global_load_dwordx4 v[140:143], v246, s[62:63]
	s_waitcnt lgkmcnt(7)
	v_mfma_f32_32x32x16_bf16 v[100:115], v[68:71], v[132:135], 0
	global_load_dwordx4 v[176:179], v247, s[64:65]
	global_load_dwordx4 v[144:147], v247, s[66:67]
	s_waitcnt lgkmcnt(6)
	v_mfma_f32_32x32x16_bf16 v[100:115], v[72:75], v[156:159], v[100:115]
	v_add3_u32 v210, s54, v188, v65
	v_add_u32_e32 v211, 0x3000, v210
	s_waitcnt lgkmcnt(5)
	v_mfma_f32_32x32x16_bf16 v[100:115], v[76:79], v[152:155], v[100:115]
	v_add_u32_e32 v210, 0x2000, v210
	s_waitcnt lgkmcnt(4)
	v_mfma_f32_32x32x16_bf16 v[100:115], v[80:83], v[148:151], v[100:115]
	s_waitcnt lgkmcnt(3)
	v_mfma_f32_32x32x16_bf16 v[116:131], v[84:87], v[132:135], 0
	s_waitcnt lgkmcnt(2)
	v_mfma_f32_32x32x16_bf16 v[116:131], v[88:91], v[156:159], v[116:131]
	s_waitcnt lgkmcnt(1)
	v_mfma_f32_32x32x16_bf16 v[116:131], v[92:95], v[152:155], v[116:131]
	s_waitcnt lgkmcnt(0)
	v_mfma_f32_32x32x16_bf16 v[116:131], v[96:99], v[148:151], v[116:131]
	ds_read_b128 v[202:205], v197 offset:4608
	ds_read_b128 v[206:209], v197 offset:4640
	ds_read_b128 v[218:221], v197 offset:4672
	v_mfma_f32_32x32x16_bf16 v[84:99], v[68:71], v[172:175], 0
	v_max3_f32 v67, v100, v101, v102
	v_max3_f32 v67, v67, v103, v104
	v_mfma_f32_32x32x16_bf16 v[84:99], v[72:75], v[168:171], v[84:99]
	v_max3_f32 v67, v67, v105, v106
	v_max3_f32 v67, v67, v107, v108
	v_mfma_f32_32x32x16_bf16 v[84:99], v[76:79], v[164:167], v[84:99]
	v_max3_f32 v67, v67, v109, v110
	v_max3_f32 v67, v67, v111, v112
	v_mfma_f32_32x32x16_bf16 v[84:99], v[80:83], v[160:163], v[84:99]
	v_max3_f32 v67, v67, v113, v114
	v_max_f32_e32 v67, v67, v115
	s_waitcnt lgkmcnt(2)
	v_mfma_f32_32x32x16_bf16 v[68:83], v[202:205], v[172:175], 0
	ds_read_b128 v[202:205], v197 offset:4704
	v_max3_f32 v182, v116, v117, v118
	v_max3_f32 v182, v182, v119, v120
	v_max3_f32 v182, v182, v121, v122
	v_max3_f32 v182, v182, v123, v124
	s_waitcnt lgkmcnt(2)
	v_mfma_f32_32x32x16_bf16 v[68:83], v[206:209], v[168:171], v[68:83]
	v_max3_f32 v182, v182, v125, v126
	v_max3_f32 v182, v182, v127, v128
	v_max3_f32 v182, v182, v129, v130
	v_max_f32_e32 v182, v182, v131
	v_max_f32_e32 v67, v67, v182
	ds_bpermute_b32 v182, v191, v67
	s_waitcnt lgkmcnt(2)
	v_mfma_f32_32x32x16_bf16 v[68:83], v[218:221], v[164:167], v[68:83]
	s_waitcnt lgkmcnt(1)
	v_mfma_f32_32x32x16_bf16 v[68:83], v[202:205], v[160:163], v[68:83]
	ds_read2_b64 v[206:209], v210 offset0:128 offset1:130
	ds_read2_b64 v[218:221], v211 offset0:160 offset1:162
	s_waitcnt lgkmcnt(2)
	v_max3_f32 v66, v216, v67, v182
	v_cmp_gt_f32_e32 vcc, v66, v216
	s_cbranch_vccz .Lattn_keep0
	v_sub_f32_e32 v182, v216, v66
	v_exp_f32_e32 v182, v182
	s_nop 0
	v_pk_mul_f32 v[48:49], v[48:49], v[182:183] op_sel_hi:[1,0]
	v_pk_mul_f32 v[50:51], v[50:51], v[182:183] op_sel_hi:[1,0]
	v_pk_mul_f32 v[52:53], v[52:53], v[182:183] op_sel_hi:[1,0]
	v_pk_mul_f32 v[54:55], v[54:55], v[182:183] op_sel_hi:[1,0]
	v_pk_mul_f32 v[56:57], v[56:57], v[182:183] op_sel_hi:[1,0]
	v_pk_mul_f32 v[58:59], v[58:59], v[182:183] op_sel_hi:[1,0]
	v_pk_mul_f32 v[60:61], v[60:61], v[182:183] op_sel_hi:[1,0]
	v_pk_mul_f32 v[62:63], v[62:63], v[182:183] op_sel_hi:[1,0]
	v_pk_mul_f32 v[16:17], v[16:17], v[182:183] op_sel_hi:[1,0]
	v_pk_mul_f32 v[18:19], v[18:19], v[182:183] op_sel_hi:[1,0]
	v_pk_mul_f32 v[20:21], v[20:21], v[182:183] op_sel_hi:[1,0]
	v_pk_mul_f32 v[22:23], v[22:23], v[182:183] op_sel_hi:[1,0]
	v_pk_mul_f32 v[24:25], v[24:25], v[182:183] op_sel_hi:[1,0]
	v_pk_mul_f32 v[26:27], v[26:27], v[182:183] op_sel_hi:[1,0]
	v_pk_mul_f32 v[28:29], v[28:29], v[182:183] op_sel_hi:[1,0]
	v_pk_mul_f32 v[30:31], v[30:31], v[182:183] op_sel_hi:[1,0]
	v_mul_f32_e32 v194, v194, v182

.Lattn_keep1:
	v_sub_f32_e32 v84, v84, v64
	v_sub_f32_e32 v85, v85, v64
	v_exp_f32_e32 v84, v84
	v_sub_f32_e32 v86, v86, v64
	v_exp_f32_e32 v85, v85
	v_add_f32_e32 v195, v195, v84
	v_sub_f32_e32 v87, v87, v64
	v_exp_f32_e32 v86, v86
	v_add_f32_e32 v195, v195, v85
	v_sub_f32_e32 v88, v88, v64
	v_exp_f32_e32 v87, v87
	v_add_f32_e32 v195, v195, v86
	v_sub_f32_e32 v89, v89, v64
	v_exp_f32_e32 v88, v88
	v_add_f32_e32 v195, v195, v87
	v_sub_f32_e32 v90, v90, v64
	v_exp_f32_e32 v89, v89
	v_add_f32_e32 v195, v195, v88
	v_sub_f32_e32 v91, v91, v64
	v_exp_f32_e32 v90, v90
	v_add_f32_e32 v195, v195, v89
	v_sub_f32_e32 v92, v92, v64
	v_exp_f32_e32 v91, v91
	v_add_f32_e32 v195, v195, v90
	v_sub_f32_e32 v93, v93, v64
	v_exp_f32_e32 v92, v92
	v_add_f32_e32 v195, v195, v91
	v_cvt_pk_bf16_f32 v84, v84, v85
	v_cvt_pk_bf16_f32 v85, v86, v87
	v_cvt_pk_bf16_f32 v86, v88, v89
	v_cvt_pk_bf16_f32 v87, v90, v91
	ds_read2_b64 v[206:209], v210 offset0:132 offset1:134
	ds_read2_b64 v[218:221], v211 offset0:164 offset1:166
	v_sub_f32_e32 v94, v94, v64
	v_exp_f32_e32 v93, v93
	s_waitcnt lgkmcnt(3)
	v_mfma_f32_32x32x16_bf16 v[32:47], v[104:107], v[84:87], v[32:47]
	v_add_f32_e32 v195, v195, v92
	v_sub_f32_e32 v95, v95, v64
	v_exp_f32_e32 v94, v94
	v_add_f32_e32 v195, v195, v93
	v_sub_f32_e32 v96, v96, v64
	v_exp_f32_e32 v95, v95
	v_add_f32_e32 v195, v195, v94
	v_sub_f32_e32 v97, v97, v64
	v_exp_f32_e32 v96, v96
	v_add_f32_e32 v195, v195, v95
	s_waitcnt lgkmcnt(2)
	v_mfma_f32_32x32x16_bf16 v[0:15], v[120:123], v[84:87], v[0:15]
	v_sub_f32_e32 v98, v98, v64
	v_exp_f32_e32 v97, v97
	v_add_f32_e32 v195, v195, v96
	v_sub_f32_e32 v99, v99, v64
	v_exp_f32_e32 v98, v98
	v_add_f32_e32 v195, v195, v97
	v_sub_f32_e32 v68, v68, v64
	v_exp_f32_e32 v99, v99
	v_add_f32_e32 v195, v195, v98
	v_sub_f32_e32 v69, v69, v64
	v_exp_f32_e32 v68, v68
	v_add_f32_e32 v195, v195, v99
	v_cvt_pk_bf16_f32 v92, v92, v93
	v_cvt_pk_bf16_f32 v93, v94, v95
	v_cvt_pk_bf16_f32 v94, v96, v97
	v_cvt_pk_bf16_f32 v95, v98, v99
	ds_read2_b64 v[128:131], v210 offset0:136 offset1:138
	ds_read2_b64 v[112:115], v211 offset0:168 offset1:170
	v_sub_f32_e32 v70, v70, v64
	v_exp_f32_e32 v69, v69
	s_waitcnt lgkmcnt(3)
	v_mfma_f32_32x32x16_bf16 v[32:47], v[206:209], v[92:95], v[32:47]
	v_add_f32_e32 v195, v195, v68
	v_sub_f32_e32 v71, v71, v64
	v_exp_f32_e32 v70, v70
	v_add_f32_e32 v195, v195, v69
	v_sub_f32_e32 v72, v72, v64
	v_exp_f32_e32 v71, v71
	v_add_f32_e32 v195, v195, v70
	v_sub_f32_e32 v73, v73, v64
	v_exp_f32_e32 v72, v72
	v_add_f32_e32 v195, v195, v71
	s_waitcnt lgkmcnt(2)
	v_mfma_f32_32x32x16_bf16 v[0:15], v[218:221], v[92:95], v[0:15]
	v_sub_f32_e32 v74, v74, v64
	v_exp_f32_e32 v73, v73
	v_add_f32_e32 v195, v195, v72
	v_sub_f32_e32 v75, v75, v64
	v_exp_f32_e32 v74, v74
	v_add_f32_e32 v195, v195, v73
	v_sub_f32_e32 v76, v76, v64
	v_exp_f32_e32 v75, v75
	v_add_f32_e32 v195, v195, v74
	v_sub_f32_e32 v77, v77, v64
	v_exp_f32_e32 v76, v76
	v_add_f32_e32 v195, v195, v75
	v_cvt_pk_bf16_f32 v68, v68, v69
	v_cvt_pk_bf16_f32 v69, v70, v71
	v_cvt_pk_bf16_f32 v70, v72, v73
	v_cvt_pk_bf16_f32 v71, v74, v75
	ds_read2_b64 v[202:205], v210 offset0:140 offset1:142
	ds_read2_b64 v[88:91], v211 offset0:172 offset1:174
	v_sub_f32_e32 v78, v78, v64
	v_exp_f32_e32 v77, v77
	s_waitcnt lgkmcnt(3)
	v_mfma_f32_32x32x16_bf16 v[32:47], v[128:131], v[68:71], v[32:47]
	v_add_f32_e32 v195, v195, v76
	v_sub_f32_e32 v79, v79, v64
	v_exp_f32_e32 v78, v78
	v_add_f32_e32 v195, v195, v77
	v_sub_f32_e32 v80, v80, v64
	v_exp_f32_e32 v79, v79
	v_add_f32_e32 v195, v195, v78
	v_sub_f32_e32 v81, v81, v64
	v_exp_f32_e32 v80, v80
	v_add_f32_e32 v195, v195, v79
	s_waitcnt lgkmcnt(2)
	v_mfma_f32_32x32x16_bf16 v[0:15], v[112:115], v[68:71], v[0:15]
	v_sub_f32_e32 v82, v82, v64
	v_exp_f32_e32 v81, v81
	v_add_f32_e32 v195, v195, v80
	v_sub_f32_e32 v83, v83, v64
	v_exp_f32_e32 v82, v82
	v_add_f32_e32 v195, v195, v81
	v_exp_f32_e32 v83, v83
	v_add_f32_e32 v195, v195, v82
	v_add_f32_e32 v195, v195, v83
	v_cvt_pk_bf16_f32 v76, v76, v77
	v_cvt_pk_bf16_f32 v77, v78, v79
	v_cvt_pk_bf16_f32 v78, v80, v81
	v_cvt_pk_bf16_f32 v79, v82, v83
	s_nop 1
	s_waitcnt lgkmcnt(1)
	v_mfma_f32_32x32x16_bf16 v[32:47], v[202:205], v[76:79], v[32:47]
	s_waitcnt lgkmcnt(0)
	v_mfma_f32_32x32x16_bf16 v[0:15], v[88:91], v[76:79], v[0:15]
	s_bitcmp1_b32 s50, 0
	s_cselect_b32 s0, 0x4600, 0
	s_add_i32 s53, s53, s33
	s_addk_i32 s52, 0x4000
	s_add_i32 s50, s50, 1
	s_add_u32 s60, s60, 0x2000
	s_addc_u32 s61, s61, 0
	s_add_u32 s62, s62, 0x2000
	s_addc_u32 s63, s63, 0
	s_add_u32 s64, s64, 0x80
	s_addc_u32 s65, s65, 0
	s_add_u32 s66, s66, 0x80
	s_addc_u32 s67, s67, 0
	s_cmpk_lg_i32 s50, 0x44
	v_add_u32_e32 v67, s0, v192
	v_add_u32_e32 v182, s0, v196
	v_add_u32_e32 v197, 0x2400, v182
	v_add_u32_e32 v182, 0x3500, v182
	s_waitcnt vmcnt(0)
	ds_write_b128 v67, v[136:139]
	ds_write_b128 v67, v[140:143] offset:4608
	ds_write2_b64 v197, v[176:177], v[178:179] offset1:1
	ds_write2_b64 v182, v[144:145], v[146:147] offset1:1
	s_waitcnt lgkmcnt(0)
	s_barrier
	s_cbranch_scc0 .LBB0_460
	v_mov_b32_e32 v217, v64
	v_mov_b32_e32 v216, v66
	s_branch .LBB0_430
